# epilogue de-serialisation: sumsq loads hoisted in P6 SwiGLU epilogue, residual base loads hoisted in P7 epilogue with counted vmcnt
# speedup vs baseline: 1.0203x; 1.0203x over previous
; #define LAS __attribute__((address_space(3)))
; #define LFENCE() asm volatile("" ::: "memory")
; template <int MODE> ...
;     const int r = lane & 31, h = lane >> 5, li = lane & 15, gg = (lane >> 4) & 1;
;     const size_t seqrow0 = (size_t)b * SEQL + res;
;     const int q0 = 32 * qt;
;     const size_t rstride = (size_t)dil * PW;
;     bf16x8 qf[4];
;     { const bf16_t* qp = PR + (seqrow0 + (size_t)(q0 + r) * dil) * PW + PC_QA + head * 64 + 8 * h;
; #pragma unroll
;       for (int s = 0; s < 4; ++s) qf[s] = *(const bf16x8*)(qp + 16 * s); }
;     f32x16 o[2];
; #pragma unroll
;     for (int dt = 0; dt < 2; ++dt)
; #pragma unroll
;         for (int i = 0; i < 16; ++i) o[dt][i] = 0.f;
;     float l = 0.f;
;     const float slope = exp2f(-(float)(head + 1)) * LOG2E * (float)dil;
;     const LAS unsigned char* trb = vl + (4 * h + (li >> 2)) * VROW + (16 * gg + 4 * (li & 3)) * 2;
;     const int first = (q0 >= 128) ? 0 : ((128 - q0) >> 5);
;     const size_t prow = (seqrow0 + (size_t)(q0 - 128 + 32 * first + (lane >> 3)) * dil) * PW + head * 64 + 8 * (lane & 7);
;     const bf16_t* kp = PR + prow + PC_KA; const bf16_t* vp = PR + prow + PC_VA;
;     LAS unsigned char* kl = vl + 4608;
;     const int stoff = (lane >> 3) * VROW + 16 * (lane & 7);
;     u32x4 kn[4], vn[4];
; #pragma unroll
;     for (int i = 0; i < 4; ++i) { kn[i] = *(const u32x4*)(kp + (size_t)(8 * i) * rstride); vn[i] = *(const u32x4*)(vp + (size_t)(8 * i) * rstride); }
;     const int rr = r - 4 * h;
; #pragma unroll 1
;     for (int kt = first; kt < 5; ++kt) {
; #pragma unroll
;         for (int i = 0; i < 4; ++i) { *(LAS u32x4*)(kl + stoff + 8 * i * VROW) = kn[i]; *(LAS u32x4*)(vl + stoff + 8 * i * VROW) = vn[i]; }
;         LFENCE();
;         if (kt < 4) {
;             kp += 32 * rstride; vp += 32 * rstride;
; #pragma unroll
;             for (int i = 0; i < 4; ++i) { kn[i] = *(const u32x4*)(kp + (size_t)(8 * i) * rstride); vn[i] = *(const u32x4*)(vp + (size_t)(8 * i) * rstride); }
;         }
;         const float fb = slope * (float)(rr + 128 - 32 * kt);
;         f32x16 s;
; #pragma unroll
;         for (int i = 0; i < 16; ++i) s[i] = slope * (float)((i & 3) + 8 * (i >> 2)) - fb;
; __global__ void __launch_bounds__(512, 2) mega(Args a) {
;     ...
;             const int br = task >> 13, tk = task & 8191, bh = tk >> 6, wq = tk & 63;
.LBB0_498:
	s_and_b32 s72, s33, 63
	s_bfe_u32 s75, s33, 0x30006
	s_cmpk_lt_u32 s33, 0x2000
	s_cselect_b64 s[88:89], -1, 0
	s_and_b64 s[0:1], s[88:89], exec
	s_mov_b32 s76, 0x1c000
	s_cselect_b32 s94, s76, 0x70000
	s_mov_b32 s76, 0x38000
	s_cselect_b32 s95, s76, 0xe0000
	s_mov_b32 s76, 0x54000
	s_cselect_b32 s1, 15, 3
	s_cselect_b32 s96, s76, 0x150000
	s_mov_b32 s76, 0x1c0000
	s_cselect_b32 s0, 4, 2
	s_cselect_b32 s92, 4, 16
	s_cselect_b32 s93, 2, 4
	s_cselect_b32 s97, 0x70000, s76
	s_and_b32 s1, s1, s33
	s_lshr_b32 s0, s72, s0
	s_lshl_b32 s72, s33, 2
	s_lshl_b32 s78, s1, 5
	s_and_b32 s72, s72, 0x7800
	v_or_b32_e32 v0, s78, v111
	s_or_b32 s0, s0, s72
	v_lshlrev_b32_e32 v0, s93, v0
	v_add_u32_e32 v96, s0, v0
	v_mad_u64_u32 v[0:1], s[76:77], v96, s74, v[100:101]
	s_add_i32 s77, s75, 1
	s_nop 0
	v_cvt_f32_ubyte0_e32 v4, s77
	s_mov_b32 s77, 0x42fc0000
	s_lshl_b32 s76, s75, 6
	s_lshl_b32 s72, s75, 7
	v_cmp_lt_f32_e32 vcc, s77, v4
	s_and_b64 s[90:91], vcc, exec
	s_cselect_b32 s79, 0xffffffc0, 0
	s_sub_i32 s77, 0x80, s78
	s_ashr_i32 s77, s77, 5
	s_cmp_lt_u32 s1, 4
	s_cselect_b32 s77, s77, 0
	v_lshl_add_u64 v[0:1], v[0:1], 0, s[72:73]
	s_lshl_b32 s90, s77, 5
	v_lshl_add_u64 v[0:1], v[0:1], 0, v[102:103]
	s_add_i32 s1, s90, s78
	global_load_dwordx4 v[48:51], v[0:1], off
	global_load_dwordx4 v[52:55], v[0:1], off offset:32
	global_load_dwordx4 v[56:59], v[0:1], off offset:64
	global_load_dwordx4 v[60:63], v[0:1], off offset:96
	v_add_u32_e32 v0, s1, v126
	v_ashrrev_i32_e32 v1, 31, v0
	v_lshlrev_b64 v[0:1], s93, v[0:1]
	s_mov_b32 s1, s73
	v_lshl_add_u64 v[0:1], v[0:1], 0, s[0:1]
	v_mad_u64_u32 v[2:3], s[0:1], v0, s74, v[98:99]
	v_mad_i32_i24 v3, v1, s74, v3
	v_lshl_add_u64 v[0:1], v[2:3], 0, s[72:73]
	s_lshl_b32 s72, s96, 1
	v_lshl_add_u64 v[2:3], v[0:1], 0, s[72:73]
	s_lshl_b32 s72, s95, 1
	s_waitcnt vmcnt(0)
	global_load_dwordx4 v[84:87], v[2:3], off offset:2048
	global_load_dwordx4 v[72:75], v[2:3], off offset:1024
	v_lshl_add_u64 v[2:3], v[0:1], 0, s[72:73]
	s_lshl_b32 s72, s94, 1
	global_load_dwordx4 v[88:91], v[2:3], off offset:2048
	global_load_dwordx4 v[76:79], v[2:3], off offset:1024
	v_lshl_add_u64 v[2:3], v[0:1], 0, s[72:73]
	global_load_dwordx4 v[92:95], v[2:3], off offset:2048
	global_load_dwordx4 v[80:83], v[2:3], off offset:1024
	global_load_dwordx4 v[68:71], v[0:1], off offset:2048
	global_load_dwordx4 v[64:67], v[0:1], off offset:1024
	v_cndmask_b32_e32 v5, 0, v128, vcc
	v_sub_f32_e32 v2, v5, v4
	v_exp_f32_e32 v2, v2
	s_mov_b64 s[0:1], 0x800
	v_lshl_add_u64 v[106:107], v[0:1], 0, s[0:1]
	s_mov_b64 s[0:1], 0x400
	v_ldexp_f32 v2, v2, s79
	v_cvt_f32_ubyte0_e32 v3, s92
	v_mul_f32_e32 v2, 0x3fb8aa3b, v2
	v_lshl_add_u64 v[108:109], v[0:1], 0, s[0:1]
	s_mov_b32 s0, 2.0
	v_mul_f32_e32 v110, v2, v3
	s_mov_b32 s1, 0x40400000
	v_pk_mul_f32 v[112:113], v[110:111], s[0:1] op_sel_hi:[0,1]
	s_mov_b32 s0, 0x41000000
	s_mov_b32 s1, 0x41100000
	v_pk_mul_f32 v[114:115], v[110:111], s[0:1] op_sel_hi:[0,1]
	s_mov_b32 s0, 0x41200000
	s_mov_b32 s1, 0x41300000
	v_mul_f32_e32 v105, 0, v110
	v_pk_mul_f32 v[116:117], v[110:111], s[0:1] op_sel_hi:[0,1]
	v_pk_mul_f32 v[118:119], v[110:111], s[80:81] op_sel_hi:[0,1]
	v_pk_mul_f32 v[120:121], v[110:111], s[82:83] op_sel_hi:[0,1]
	v_pk_mul_f32 v[122:123], v[110:111], s[84:85] op_sel_hi:[0,1]
	v_pk_mul_f32 v[124:125], v[110:111], s[86:87] op_sel_hi:[0,1]
	v_subrev_u32_e32 v135, s90, v127
	s_lshl_b32 s72, s97, 1
	s_lshl_b32 s90, s94, 1
	s_lshl_b32 s92, s95, 1
	s_lshl_b32 s94, s96, 1
	v_mov_b32_e32 v134, v97
	v_mov_b32_e32 v16, v97
	v_mov_b32_e32 v17, v97
	v_mov_b32_e32 v18, v97
	v_mov_b32_e32 v19, v97
	v_mov_b32_e32 v20, v97
	v_mov_b32_e32 v21, v97
	v_mov_b32_e32 v22, v97
	v_mov_b32_e32 v23, v97
	v_mov_b32_e32 v24, v97
	v_mov_b32_e32 v25, v97
	v_mov_b32_e32 v26, v97
	v_mov_b32_e32 v27, v97
	v_mov_b32_e32 v28, v97
	v_mov_b32_e32 v29, v97
	v_mov_b32_e32 v30, v97
	v_mov_b32_e32 v31, v97
	v_mov_b32_e32 v0, v97
	v_mov_b32_e32 v1, v97
	v_mov_b32_e32 v2, v97
	v_mov_b32_e32 v3, v97
	v_mov_b32_e32 v4, v97
	v_mov_b32_e32 v5, v97
	v_mov_b32_e32 v6, v97
	v_mov_b32_e32 v7, v97
	v_mov_b32_e32 v8, v97
	v_mov_b32_e32 v9, v97
	v_mov_b32_e32 v10, v97
	v_mov_b32_e32 v11, v97
	v_mov_b32_e32 v12, v97
	v_mov_b32_e32 v13, v97
	v_mov_b32_e32 v14, v97
	v_mov_b32_e32 v15, v97

; __device__ __forceinline__ unsigned pk2(float lo, float hi) { return pg8::cvt_pk_bf16(lo, hi); }
; __device__ __forceinline__ float silu_f(float x) { return x * sigmoid_f(x); }
;     __device__ __forceinline__ void operator()(const f32x4 (&acc)[2][2][4][2], const pg8::Unit& u, int wr, int wc, int fr, int fq) const {
;         const int row0 = u.pm * 256 + wr * 64 + fr, col = u.pn * 128 + wc * 32 + 8 * fq;
; #pragma unroll
;         for (int ai = 0; ai < 2; ++ai)
; #pragma unroll
;             for (int m = 0; m < 4; ++m) {
;                 const int row = row0 + ai * 128 + m * 16;
;                 const float rs = sumsq ? rsqrtf(sumsq[row] * (1.f / 1024.f) + EPS) : 1.f;
;                 float o[8];
; #pragma unroll
;                 for (int n = 0; n < 2; ++n)
; #pragma unroll
;                     for (int e = 0; e < 4; ++e) { const float g = acc[ai][0][m][n][e] * rs, up = acc[ai][1][m][n][e] * rs; o[4 * n + e] = silu_f(g) * up; }
;                 u32x4 w; w.x = pk2(o[0], o[1]); w.y = pk2(o[2], o[3]); w.z = pk2(o[4], o[5]); w.w = pk2(o[6], o[7]);
;                 *(u32x4*)(H + (size_t)row * DFF + col) = w;
;             }
.LBB0_785:
	v_lshl_add_u32 v144, s0, 8, v148
	v_ashrrev_i32_e32 v145, 31, v144
	v_lshl_add_u64 v[146:147], v[144:145], 2, s[10:11]
	global_load_dword v145, v[146:147], off
	global_load_dword v236, v[146:147], off offset:64
	global_load_dword v237, v[146:147], off offset:128
	global_load_dword v238, v[146:147], off offset:192
	global_load_dword v239, v[146:147], off offset:512
	global_load_dword v240, v[146:147], off offset:576
	global_load_dword v241, v[146:147], off offset:640
	global_load_dword v242, v[146:147], off offset:704
	v_lshl_or_b32 v156, s1, 7, v150
	v_readlane_b32 s0, v235, 33
	v_mov_b32_e32 v161, v114
	v_mov_b32_e32 v114, v123
	v_readlane_b32 s1, v235, 34
	v_mov_b32_e32 v158, v124
	v_mov_b32_e32 v159, v116
	v_mov_b32_e32 v116, v125
	v_mov_b32_e32 v124, v126
	v_mov_b32_e32 v125, v118
	v_mov_b32_e32 v118, v127
	v_mov_b32_e32 v126, v120
	v_mov_b32_e32 v127, v112
	v_mov_b32_e32 v112, v121
	v_mov_b32_e32 v160, v122
	v_mov_b64_e32 v[120:121], s[0:1]
	v_ashrrev_i32_e32 v157, 31, v156
	v_or_b32_e32 v164, 16, v144
	v_mad_i64_i32 v[162:163], s[0:1], v144, s46, v[120:121]
	v_lshlrev_b64 v[122:123], 1, v[156:157]
	v_ashrrev_i32_e32 v165, 31, v164
	v_lshl_add_u64 v[156:157], v[162:163], 0, v[122:123]
	v_lshl_add_u64 v[162:163], v[164:165], 2, s[10:11]
	s_waitcnt vmcnt(0)
	v_fmamk_f32 v145, v145, 0x3a800000, v154
	v_mul_f32_e32 v155, 0x4b800000, v145
	v_cmp_gt_f32_e32 vcc, s45, v145
	s_nop 1
	v_cndmask_b32_e32 v145, v145, v155, vcc
	v_rsq_f32_e32 v145, v145
	s_nop 0
	v_mul_f32_e32 v155, 0x45800000, v145
	v_cndmask_b32_e32 v166, v145, v155, vcc
	v_pk_mul_f32 v[114:115], v[114:115], v[166:167] op_sel_hi:[1,0]
	v_pk_mul_f32 v[158:159], v[158:159], v[166:167] op_sel_hi:[1,0]
	v_pk_mul_f32 v[116:117], v[116:117], v[166:167] op_sel_hi:[1,0]
	v_pk_mul_f32 v[124:125], v[124:125], v[166:167] op_sel_hi:[1,0]
	v_pk_mul_f32 v[118:119], v[118:119], v[166:167] op_sel_hi:[1,0]
	v_pk_mul_f32 v[126:127], v[126:127], v[166:167] op_sel_hi:[1,0]
	v_pk_mul_f32 v[112:113], v[112:113], v[166:167] op_sel_hi:[1,0]
	v_pk_mul_f32 v[160:161], v[160:161], v[166:167] op_sel_hi:[1,0]
	v_mul_f32_e32 v170, 0xbfb8aa3b, v115
	v_mul_f32_e32 v145, 0xbfb8aa3b, v159
	v_mul_f32_e32 v155, 0xbfb8aa3b, v117
	v_mul_f32_e32 v165, 0xbfb8aa3b, v125
	v_mul_f32_e32 v166, 0xbfb8aa3b, v119
	v_mul_f32_e32 v167, 0xbfb8aa3b, v127
	v_mul_f32_e32 v168, 0xbfb8aa3b, v113
	v_mul_f32_e32 v169, 0xbfb8aa3b, v161
	v_exp_f32_e32 v170, v170
	v_exp_f32_e32 v145, v145
	v_exp_f32_e32 v155, v155
	v_exp_f32_e32 v165, v165
	v_exp_f32_e32 v166, v166
	v_exp_f32_e32 v167, v167
	v_exp_f32_e32 v168, v168
	v_exp_f32_e32 v169, v169
	v_add_f32_e32 v170, 1.0, v170
	v_add_f32_e32 v145, 1.0, v145
	v_add_f32_e32 v155, 1.0, v155
	v_add_f32_e32 v165, 1.0, v165
	v_add_f32_e32 v166, 1.0, v166
	v_add_f32_e32 v167, 1.0, v167
	v_add_f32_e32 v168, 1.0, v168
	v_add_f32_e32 v169, 1.0, v169
	v_rcp_f32_e32 v170, v170
	v_rcp_f32_e32 v145, v145
	v_rcp_f32_e32 v155, v155
	v_rcp_f32_e32 v165, v165
	v_rcp_f32_e32 v166, v166
	v_rcp_f32_e32 v167, v167
	v_rcp_f32_e32 v168, v168
	v_rcp_f32_e32 v169, v169
	v_mul_f32_e32 v115, v115, v170
	v_mul_f32_e32 v145, v159, v145
	v_mul_f32_e32 v117, v117, v155
	v_mul_f32_e32 v125, v125, v165
	v_mul_f32_e32 v119, v119, v166
	v_mul_f32_e32 v127, v127, v167
	v_mul_f32_e32 v113, v113, v168
	v_mul_f32_e32 v155, v161, v169
	v_mul_f32_e32 v115, v114, v115
	v_mul_f32_e32 v145, v158, v145
	v_mul_f32_e32 v116, v116, v117
	v_mul_f32_e32 v117, v124, v125
	v_mul_f32_e32 v118, v118, v119
	v_mul_f32_e32 v119, v126, v127
	v_mul_f32_e32 v124, v112, v113
	v_mul_f32_e32 v125, v160, v155
	v_cvt_pk_bf16_f32 v112, v145, v116
	v_cvt_pk_bf16_f32 v113, v117, v118
	v_cvt_pk_bf16_f32 v114, v119, v124
	v_cvt_pk_bf16_f32 v115, v125, v115
	global_store_dwordx4 v[156:157], v[112:115], off
	s_nop 0
	s_nop 0
	v_mov_b32_e32 v113, v100
	v_mov_b32_e32 v100, v109
	v_mov_b32_e32 v109, v102
	v_mov_b32_e32 v102, v111
	v_mov_b32_e32 v111, v96
	v_mov_b32_e32 v96, v105
	v_mov_b32_e32 v105, v98
	v_mov_b32_e32 v98, v107
	v_mov_b32_e32 v112, v108
	v_mov_b32_e32 v108, v110
	v_mov_b32_e32 v110, v104
	v_mov_b32_e32 v104, v106
	v_or_b32_e32 v106, 32, v144
	v_mad_i64_i32 v[114:115], s[0:1], v164, s46, v[120:121]
	v_lshl_add_u64 v[114:115], v[114:115], 0, v[122:123]
	s_nop 0
	v_fmamk_f32 v107, v236, 0x3a800000, v154
	v_mul_f32_e32 v116, 0x4b800000, v107
	v_cmp_gt_f32_e32 vcc, s45, v107
	s_nop 1
	v_cndmask_b32_e32 v107, v107, v116, vcc
	v_rsq_f32_e32 v118, v107
	v_ashrrev_i32_e32 v107, 31, v106
	v_lshl_add_u64 v[116:117], v[106:107], 2, s[10:11]
	v_mul_f32_e32 v107, 0x45800000, v118
	v_cndmask_b32_e32 v118, v118, v107, vcc
	v_pk_mul_f32 v[98:99], v[98:99], v[118:119] op_sel_hi:[1,0]
	v_pk_mul_f32 v[112:113], v[112:113], v[118:119] op_sel_hi:[1,0]
	v_pk_mul_f32 v[100:101], v[100:101], v[118:119] op_sel_hi:[1,0]
	v_pk_mul_f32 v[108:109], v[108:109], v[118:119] op_sel_hi:[1,0]
	v_pk_mul_f32 v[102:103], v[102:103], v[118:119] op_sel_hi:[1,0]
	v_pk_mul_f32 v[110:111], v[110:111], v[118:119] op_sel_hi:[1,0]
	v_pk_mul_f32 v[96:97], v[96:97], v[118:119] op_sel_hi:[1,0]
	v_pk_mul_f32 v[104:105], v[104:105], v[118:119] op_sel_hi:[1,0]
	v_mul_f32_e32 v145, 0xbfb8aa3b, v99
	v_mul_f32_e32 v107, 0xbfb8aa3b, v113
	v_mul_f32_e32 v118, 0xbfb8aa3b, v101
	v_mul_f32_e32 v119, 0xbfb8aa3b, v109
	v_mul_f32_e32 v124, 0xbfb8aa3b, v103
	v_mul_f32_e32 v125, 0xbfb8aa3b, v111
	v_mul_f32_e32 v126, 0xbfb8aa3b, v97
	v_mul_f32_e32 v127, 0xbfb8aa3b, v105
	v_exp_f32_e32 v145, v145
	v_exp_f32_e32 v107, v107
	v_exp_f32_e32 v118, v118
	v_exp_f32_e32 v119, v119
	v_exp_f32_e32 v124, v124
	v_exp_f32_e32 v125, v125
	v_exp_f32_e32 v126, v126
	v_exp_f32_e32 v127, v127
	v_add_f32_e32 v145, 1.0, v145
; __device__ __forceinline__ unsigned pk2(float lo, float hi) { return pg8::cvt_pk_bf16(lo, hi); }
; __device__ __forceinline__ float silu_f(float x) { return x * sigmoid_f(x); }
;     __device__ __forceinline__ void operator()(const f32x4 (&acc)[2][2][4][2], const pg8::Unit& u, int wr, int wc, int fr, int fq) const {
;         const int row0 = u.pm * 256 + wr * 64 + fr, col = u.pn * 128 + wc * 32 + 8 * fq;
; #pragma unroll
;         for (int ai = 0; ai < 2; ++ai)
; #pragma unroll
;             for (int m = 0; m < 4; ++m) {
;                 const int row = row0 + ai * 128 + m * 16;
;                 const float rs = sumsq ? rsqrtf(sumsq[row] * (1.f / 1024.f) + EPS) : 1.f;
;                 float o[8];
; #pragma unroll
;                 for (int n = 0; n < 2; ++n)
; #pragma unroll
;                     for (int e = 0; e < 4; ++e) { const float g = acc[ai][0][m][n][e] * rs, up = acc[ai][1][m][n][e] * rs; o[4 * n + e] = silu_f(g) * up; }
;                 u32x4 w; w.x = pk2(o[0], o[1]); w.y = pk2(o[2], o[3]); w.z = pk2(o[4], o[5]); w.w = pk2(o[6], o[7]);
;                 *(u32x4*)(H + (size_t)row * DFF + col) = w;
;             }
	v_add_f32_e32 v107, 1.0, v107
	v_add_f32_e32 v118, 1.0, v118
	v_add_f32_e32 v119, 1.0, v119
	v_add_f32_e32 v124, 1.0, v124
	v_add_f32_e32 v125, 1.0, v125
	v_add_f32_e32 v126, 1.0, v126
	v_add_f32_e32 v127, 1.0, v127
	v_rcp_f32_e32 v145, v145
	v_rcp_f32_e32 v107, v107
	v_rcp_f32_e32 v118, v118
	v_rcp_f32_e32 v119, v119
	v_rcp_f32_e32 v124, v124
	v_rcp_f32_e32 v125, v125
	v_rcp_f32_e32 v126, v126
	v_rcp_f32_e32 v127, v127
	v_mul_f32_e32 v99, v99, v145
	v_mul_f32_e32 v107, v113, v107
	v_mul_f32_e32 v101, v101, v118
	v_mul_f32_e32 v109, v109, v119
	v_mul_f32_e32 v103, v103, v124
	v_mul_f32_e32 v111, v111, v125
	v_mul_f32_e32 v97, v97, v126
	v_mul_f32_e32 v105, v105, v127
	v_mul_f32_e32 v99, v98, v99
	v_mul_f32_e32 v107, v112, v107
	v_mul_f32_e32 v100, v100, v101
	v_mul_f32_e32 v101, v108, v109
	v_mul_f32_e32 v102, v102, v103
	v_mul_f32_e32 v103, v110, v111
	v_mul_f32_e32 v108, v96, v97
	v_mul_f32_e32 v104, v104, v105
	v_cvt_pk_bf16_f32 v96, v107, v100
	v_cvt_pk_bf16_f32 v97, v101, v102
	v_cvt_pk_bf16_f32 v98, v103, v108
	v_cvt_pk_bf16_f32 v99, v104, v99
	global_store_dwordx4 v[114:115], v[96:99], off
	s_nop 0
	s_nop 0
	v_mov_b32_e32 v97, v84
	v_mov_b32_e32 v84, v93
	v_mov_b32_e32 v93, v86
	v_mov_b32_e32 v86, v95
	v_mov_b32_e32 v95, v80
	v_mov_b32_e32 v80, v89
	v_mov_b32_e32 v89, v82
	v_mov_b32_e32 v82, v91
	v_mov_b32_e32 v96, v92
	v_mov_b32_e32 v92, v94
	v_mov_b32_e32 v94, v88
	v_mov_b32_e32 v88, v90
	v_or_b32_e32 v90, 48, v144
	v_mad_i64_i32 v[98:99], s[0:1], v106, s46, v[120:121]
	v_lshl_add_u64 v[98:99], v[98:99], 0, v[122:123]
	s_nop 0
	v_fmamk_f32 v91, v237, 0x3a800000, v154
	v_mul_f32_e32 v100, 0x4b800000, v91
	v_cmp_gt_f32_e32 vcc, s45, v91
	s_nop 1
	v_cndmask_b32_e32 v91, v91, v100, vcc
	v_rsq_f32_e32 v102, v91
	v_ashrrev_i32_e32 v91, 31, v90
	v_lshl_add_u64 v[100:101], v[90:91], 2, s[10:11]
	v_mul_f32_e32 v91, 0x45800000, v102
	v_cndmask_b32_e32 v102, v102, v91, vcc
	v_pk_mul_f32 v[82:83], v[82:83], v[102:103] op_sel_hi:[1,0]
	v_pk_mul_f32 v[96:97], v[96:97], v[102:103] op_sel_hi:[1,0]
	v_pk_mul_f32 v[84:85], v[84:85], v[102:103] op_sel_hi:[1,0]
	v_pk_mul_f32 v[92:93], v[92:93], v[102:103] op_sel_hi:[1,0]
	v_pk_mul_f32 v[86:87], v[86:87], v[102:103] op_sel_hi:[1,0]
	v_pk_mul_f32 v[94:95], v[94:95], v[102:103] op_sel_hi:[1,0]
	v_pk_mul_f32 v[80:81], v[80:81], v[102:103] op_sel_hi:[1,0]
	v_pk_mul_f32 v[88:89], v[88:89], v[102:103] op_sel_hi:[1,0]
	v_mul_f32_e32 v108, 0xbfb8aa3b, v83
	v_mul_f32_e32 v91, 0xbfb8aa3b, v97
	v_mul_f32_e32 v102, 0xbfb8aa3b, v85
	v_mul_f32_e32 v103, 0xbfb8aa3b, v93
	v_mul_f32_e32 v104, 0xbfb8aa3b, v87
	v_mul_f32_e32 v105, 0xbfb8aa3b, v95
	v_mul_f32_e32 v106, 0xbfb8aa3b, v81
	v_mul_f32_e32 v107, 0xbfb8aa3b, v89
	v_exp_f32_e32 v108, v108
	v_exp_f32_e32 v91, v91
	v_exp_f32_e32 v102, v102
	v_exp_f32_e32 v103, v103
	v_exp_f32_e32 v104, v104
	v_exp_f32_e32 v105, v105
	v_exp_f32_e32 v106, v106
	v_exp_f32_e32 v107, v107
	v_add_f32_e32 v108, 1.0, v108
	v_add_f32_e32 v91, 1.0, v91
	v_add_f32_e32 v102, 1.0, v102
	v_add_f32_e32 v103, 1.0, v103
	v_add_f32_e32 v104, 1.0, v104
	v_add_f32_e32 v105, 1.0, v105
	v_add_f32_e32 v106, 1.0, v106
	v_add_f32_e32 v107, 1.0, v107
	v_rcp_f32_e32 v108, v108
	v_rcp_f32_e32 v91, v91
	v_rcp_f32_e32 v102, v102
	v_rcp_f32_e32 v103, v103
	v_rcp_f32_e32 v104, v104
	v_rcp_f32_e32 v105, v105
	v_rcp_f32_e32 v106, v106
	v_rcp_f32_e32 v107, v107
	v_mul_f32_e32 v83, v83, v108
	v_mul_f32_e32 v91, v97, v91
	v_mul_f32_e32 v85, v85, v102
	v_mul_f32_e32 v93, v93, v103
	v_mul_f32_e32 v87, v87, v104
	v_mul_f32_e32 v95, v95, v105
	v_mul_f32_e32 v81, v81, v106
	v_mul_f32_e32 v89, v89, v107
	v_mul_f32_e32 v83, v82, v83
	v_mul_f32_e32 v91, v96, v91
	v_mul_f32_e32 v84, v84, v85
	v_mul_f32_e32 v85, v92, v93
	v_mul_f32_e32 v86, v86, v87
	v_mul_f32_e32 v87, v94, v95
	v_mul_f32_e32 v92, v80, v81
	v_mul_f32_e32 v88, v88, v89
	v_cvt_pk_bf16_f32 v80, v91, v84
	v_cvt_pk_bf16_f32 v81, v85, v86
	v_cvt_pk_bf16_f32 v82, v87, v92
	v_cvt_pk_bf16_f32 v83, v88, v83
	global_store_dwordx4 v[98:99], v[80:83], off
	s_nop 0
	s_nop 0
	v_mov_b32_e32 v80, v76
	v_mov_b32_e32 v76, v78
	v_mov_b32_e32 v78, v68
	v_mov_b32_e32 v68, v70
	v_mov_b32_e32 v81, v72
	v_mov_b32_e32 v72, v77
	v_mov_b32_e32 v77, v74
	v_mov_b32_e32 v74, v79
	v_mov_b32_e32 v79, v64
	v_mov_b32_e32 v64, v69
	v_mov_b32_e32 v69, v66
	v_mov_b32_e32 v66, v71
	s_nop 0
	v_fmamk_f32 v70, v238, 0x3a800000, v154
	v_mul_f32_e32 v71, 0x4b800000, v70
	v_cmp_gt_f32_e32 vcc, s45, v70
	s_nop 1
	v_cndmask_b32_e32 v70, v70, v71, vcc
	v_rsq_f32_e32 v82, v70
	v_mad_i64_i32 v[70:71], s[0:1], v90, s46, v[120:121]
	v_lshl_add_u64 v[70:71], v[70:71], 0, v[122:123]
	v_mul_f32_e32 v83, 0x45800000, v82
	v_cndmask_b32_e32 v82, v82, v83, vcc
	v_pk_mul_f32 v[66:67], v[66:67], v[82:83] op_sel_hi:[1,0]
	v_pk_mul_f32 v[80:81], v[80:81], v[82:83] op_sel_hi:[1,0]
	v_pk_mul_f32 v[72:73], v[72:73], v[82:83] op_sel_hi:[1,0]
	v_pk_mul_f32 v[76:77], v[76:77], v[82:83] op_sel_hi:[1,0]
	v_pk_mul_f32 v[74:75], v[74:75], v[82:83] op_sel_hi:[1,0]
	v_pk_mul_f32 v[78:79], v[78:79], v[82:83] op_sel_hi:[1,0]
	v_pk_mul_f32 v[64:65], v[64:65], v[82:83] op_sel_hi:[1,0]
	v_pk_mul_f32 v[68:69], v[68:69], v[82:83] op_sel_hi:[1,0]
	v_mul_f32_e32 v89, 0xbfb8aa3b, v67
	v_mul_f32_e32 v82, 0xbfb8aa3b, v81
	v_mul_f32_e32 v83, 0xbfb8aa3b, v73
	v_mul_f32_e32 v84, 0xbfb8aa3b, v77
	v_mul_f32_e32 v85, 0xbfb8aa3b, v75
	v_mul_f32_e32 v86, 0xbfb8aa3b, v79
	v_mul_f32_e32 v87, 0xbfb8aa3b, v65
	v_mul_f32_e32 v88, 0xbfb8aa3b, v69
	v_exp_f32_e32 v89, v89
	v_exp_f32_e32 v82, v82
	v_exp_f32_e32 v83, v83
	v_exp_f32_e32 v84, v84
	v_exp_f32_e32 v85, v85
	v_exp_f32_e32 v86, v86
	v_exp_f32_e32 v87, v87
	v_exp_f32_e32 v88, v88
	v_add_f32_e32 v89, 1.0, v89
; __device__ __forceinline__ unsigned pk2(float lo, float hi) { return pg8::cvt_pk_bf16(lo, hi); }
; __device__ __forceinline__ float silu_f(float x) { return x * sigmoid_f(x); }
;     __device__ __forceinline__ void operator()(const f32x4 (&acc)[2][2][4][2], const pg8::Unit& u, int wr, int wc, int fr, int fq) const {
;         const int row0 = u.pm * 256 + wr * 64 + fr, col = u.pn * 128 + wc * 32 + 8 * fq;
; #pragma unroll
;         for (int ai = 0; ai < 2; ++ai)
; #pragma unroll
;             for (int m = 0; m < 4; ++m) {
;                 const int row = row0 + ai * 128 + m * 16;
;                 const float rs = sumsq ? rsqrtf(sumsq[row] * (1.f / 1024.f) + EPS) : 1.f;
;                 float o[8];
; #pragma unroll
;                 for (int n = 0; n < 2; ++n)
; #pragma unroll
;                     for (int e = 0; e < 4; ++e) { const float g = acc[ai][0][m][n][e] * rs, up = acc[ai][1][m][n][e] * rs; o[4 * n + e] = silu_f(g) * up; }
;                 u32x4 w; w.x = pk2(o[0], o[1]); w.y = pk2(o[2], o[3]); w.z = pk2(o[4], o[5]); w.w = pk2(o[6], o[7]);
;                 *(u32x4*)(H + (size_t)row * DFF + col) = w;
;             }
	v_add_f32_e32 v82, 1.0, v82
	v_add_f32_e32 v83, 1.0, v83
	v_add_f32_e32 v84, 1.0, v84
	v_add_f32_e32 v85, 1.0, v85
	v_add_f32_e32 v86, 1.0, v86
	v_add_f32_e32 v87, 1.0, v87
	v_add_f32_e32 v88, 1.0, v88
	v_rcp_f32_e32 v89, v89
	v_rcp_f32_e32 v82, v82
	v_rcp_f32_e32 v83, v83
	v_rcp_f32_e32 v84, v84
	v_rcp_f32_e32 v85, v85
	v_rcp_f32_e32 v86, v86
	v_rcp_f32_e32 v87, v87
	v_rcp_f32_e32 v88, v88
	v_mul_f32_e32 v67, v67, v89
	v_mul_f32_e32 v81, v81, v82
	v_mul_f32_e32 v73, v73, v83
	v_mul_f32_e32 v77, v77, v84
	v_mul_f32_e32 v75, v75, v85
	v_mul_f32_e32 v79, v79, v86
	v_mul_f32_e32 v65, v65, v87
	v_mul_f32_e32 v69, v69, v88
	v_mul_f32_e32 v67, v66, v67
	v_mul_f32_e32 v80, v80, v81
	v_mul_f32_e32 v72, v72, v73
	v_mul_f32_e32 v73, v76, v77
	v_mul_f32_e32 v74, v74, v75
	v_mul_f32_e32 v75, v78, v79
	v_mul_f32_e32 v76, v64, v65
	v_mul_f32_e32 v68, v68, v69
	v_cvt_pk_bf16_f32 v64, v80, v72
	v_cvt_pk_bf16_f32 v65, v73, v74
	v_cvt_pk_bf16_f32 v66, v75, v76
	v_cvt_pk_bf16_f32 v67, v68, v67
	global_store_dwordx4 v[70:71], v[64:67], off
	s_nop 0
	s_nop 0
	v_mov_b32_e32 v65, v56
	v_mov_b32_e32 v56, v61
	v_mov_b32_e32 v61, v58
	v_mov_b32_e32 v58, v63
	v_mov_b32_e32 v63, v48
	v_mov_b32_e32 v48, v53
	v_mov_b32_e32 v53, v50
	v_mov_b32_e32 v50, v55
	v_mov_b32_e32 v64, v60
	v_mov_b32_e32 v60, v62
	v_mov_b32_e32 v62, v52
	v_mov_b32_e32 v52, v54
	v_add_u32_e32 v54, 0x80, v144
	s_nop 0
	v_fmamk_f32 v55, v239, 0x3a800000, v154
	v_mul_f32_e32 v66, 0x4b800000, v55
	v_cmp_gt_f32_e32 vcc, s45, v55
	s_nop 1
	v_cndmask_b32_e32 v55, v55, v66, vcc
	v_rsq_f32_e32 v66, v55
	v_mad_i64_i32 v[54:55], s[0:1], v54, s46, v[120:121]
	v_lshl_add_u64 v[54:55], v[54:55], 0, v[122:123]
	v_mul_f32_e32 v67, 0x45800000, v66
	v_cndmask_b32_e32 v66, v66, v67, vcc
	v_pk_mul_f32 v[50:51], v[50:51], v[66:67] op_sel_hi:[1,0]
	v_pk_mul_f32 v[64:65], v[64:65], v[66:67] op_sel_hi:[1,0]
	v_pk_mul_f32 v[56:57], v[56:57], v[66:67] op_sel_hi:[1,0]
	v_pk_mul_f32 v[60:61], v[60:61], v[66:67] op_sel_hi:[1,0]
	v_pk_mul_f32 v[58:59], v[58:59], v[66:67] op_sel_hi:[1,0]
	v_pk_mul_f32 v[62:63], v[62:63], v[66:67] op_sel_hi:[1,0]
	v_pk_mul_f32 v[48:49], v[48:49], v[66:67] op_sel_hi:[1,0]
	v_pk_mul_f32 v[52:53], v[52:53], v[66:67] op_sel_hi:[1,0]
	v_mul_f32_e32 v73, 0xbfb8aa3b, v51
	v_mul_f32_e32 v66, 0xbfb8aa3b, v65
	v_mul_f32_e32 v67, 0xbfb8aa3b, v57
	v_mul_f32_e32 v68, 0xbfb8aa3b, v61
	v_mul_f32_e32 v69, 0xbfb8aa3b, v59
	v_mul_f32_e32 v70, 0xbfb8aa3b, v63
	v_mul_f32_e32 v71, 0xbfb8aa3b, v49
	v_mul_f32_e32 v72, 0xbfb8aa3b, v53
	v_exp_f32_e32 v73, v73
	v_exp_f32_e32 v66, v66
	v_exp_f32_e32 v67, v67
	v_exp_f32_e32 v68, v68
	v_exp_f32_e32 v69, v69
	v_exp_f32_e32 v70, v70
	v_exp_f32_e32 v71, v71
	v_exp_f32_e32 v72, v72
	v_add_f32_e32 v73, 1.0, v73
	v_add_f32_e32 v66, 1.0, v66
	v_add_f32_e32 v67, 1.0, v67
	v_add_f32_e32 v68, 1.0, v68
	v_add_f32_e32 v69, 1.0, v69
	v_add_f32_e32 v70, 1.0, v70
	v_add_f32_e32 v71, 1.0, v71
	v_add_f32_e32 v72, 1.0, v72
	v_rcp_f32_e32 v73, v73
	v_rcp_f32_e32 v66, v66
	v_rcp_f32_e32 v67, v67
	v_rcp_f32_e32 v68, v68
	v_rcp_f32_e32 v69, v69
	v_rcp_f32_e32 v70, v70
	v_rcp_f32_e32 v71, v71
	v_rcp_f32_e32 v72, v72
	v_mul_f32_e32 v51, v51, v73
	v_mul_f32_e32 v65, v65, v66
	v_mul_f32_e32 v57, v57, v67
	v_mul_f32_e32 v61, v61, v68
	v_mul_f32_e32 v59, v59, v69
	v_mul_f32_e32 v63, v63, v70
	v_mul_f32_e32 v49, v49, v71
	v_mul_f32_e32 v53, v53, v72
	v_mul_f32_e32 v51, v50, v51
	v_mul_f32_e32 v64, v64, v65
	v_mul_f32_e32 v56, v56, v57
	v_mul_f32_e32 v57, v60, v61
	v_mul_f32_e32 v58, v58, v59
	v_mul_f32_e32 v59, v62, v63
	v_mul_f32_e32 v60, v48, v49
	v_mul_f32_e32 v52, v52, v53
	v_cvt_pk_bf16_f32 v48, v64, v56
	v_cvt_pk_bf16_f32 v49, v57, v58
	v_cvt_pk_bf16_f32 v50, v59, v60
	v_cvt_pk_bf16_f32 v51, v52, v51
	global_store_dwordx4 v[54:55], v[48:51], off
	s_nop 0
	s_nop 0
	v_mov_b32_e32 v49, v40
	v_mov_b32_e32 v40, v45
	v_mov_b32_e32 v45, v42
	v_mov_b32_e32 v42, v47
	v_mov_b32_e32 v47, v32
	v_mov_b32_e32 v32, v37
	v_mov_b32_e32 v37, v34
	v_mov_b32_e32 v34, v39
	v_mov_b32_e32 v48, v44
	v_mov_b32_e32 v44, v46
	v_mov_b32_e32 v46, v36
	v_mov_b32_e32 v36, v38
	v_add_u32_e32 v38, 0x90, v144
	s_nop 0
	v_fmamk_f32 v39, v240, 0x3a800000, v154
	v_mul_f32_e32 v50, 0x4b800000, v39
	v_cmp_gt_f32_e32 vcc, s45, v39
	s_nop 1
	v_cndmask_b32_e32 v39, v39, v50, vcc
	v_rsq_f32_e32 v50, v39
	v_mad_i64_i32 v[38:39], s[0:1], v38, s46, v[120:121]
	v_lshl_add_u64 v[38:39], v[38:39], 0, v[122:123]
	v_mul_f32_e32 v51, 0x45800000, v50
	v_cndmask_b32_e32 v50, v50, v51, vcc
	v_pk_mul_f32 v[34:35], v[34:35], v[50:51] op_sel_hi:[1,0]
	v_pk_mul_f32 v[48:49], v[48:49], v[50:51] op_sel_hi:[1,0]
	v_pk_mul_f32 v[40:41], v[40:41], v[50:51] op_sel_hi:[1,0]
	v_pk_mul_f32 v[44:45], v[44:45], v[50:51] op_sel_hi:[1,0]
	v_pk_mul_f32 v[42:43], v[42:43], v[50:51] op_sel_hi:[1,0]
	v_pk_mul_f32 v[46:47], v[46:47], v[50:51] op_sel_hi:[1,0]
	v_pk_mul_f32 v[32:33], v[32:33], v[50:51] op_sel_hi:[1,0]
	v_pk_mul_f32 v[36:37], v[36:37], v[50:51] op_sel_hi:[1,0]
	v_mul_f32_e32 v57, 0xbfb8aa3b, v35
	v_mul_f32_e32 v50, 0xbfb8aa3b, v49
	v_mul_f32_e32 v51, 0xbfb8aa3b, v41
	v_mul_f32_e32 v52, 0xbfb8aa3b, v45
	v_mul_f32_e32 v53, 0xbfb8aa3b, v43
	v_mul_f32_e32 v54, 0xbfb8aa3b, v47
	v_mul_f32_e32 v55, 0xbfb8aa3b, v33
	v_mul_f32_e32 v56, 0xbfb8aa3b, v37
	v_exp_f32_e32 v57, v57
	v_exp_f32_e32 v50, v50
	v_exp_f32_e32 v51, v51
	v_exp_f32_e32 v52, v52
	v_exp_f32_e32 v53, v53
	v_exp_f32_e32 v54, v54
	v_exp_f32_e32 v55, v55
	v_exp_f32_e32 v56, v56
	v_add_f32_e32 v57, 1.0, v57
	v_add_f32_e32 v50, 1.0, v50
	v_add_f32_e32 v51, 1.0, v51
	v_add_f32_e32 v52, 1.0, v52
	v_add_f32_e32 v53, 1.0, v53
	v_add_f32_e32 v54, 1.0, v54
	v_add_f32_e32 v55, 1.0, v55
	v_add_f32_e32 v56, 1.0, v56
; #define PG8_BAR __builtin_amdgcn_s_barrier()
; __device__ __forceinline__ unsigned pk2(float lo, float hi) { return pg8::cvt_pk_bf16(lo, hi); }
; __device__ __forceinline__ float silu_f(float x) { return x * sigmoid_f(x); }
; template <class Epi, class Sched, bool ALIGN_EPI = false, bool SP2 = false>
; __device__ __forceinline__ void gemm_phase(PG8_LAS unsigned char* lds, const Gemm g, const Sched& S, const Epi& E) {
;     ...
;         if (!has_next) break;
; #pragma unroll
;         for (int a = 0; a < 2; ++a)
; #pragma unroll
;             for (int b = 0; b < 2; ++b)
; #pragma unroll
;                 for (int m = 0; m < 4; ++m)
; #pragma unroll
;                     for (int n = 0; n < 2; ++n) acc[a][b][m][n] = (f32x4){0.f, 0.f, 0.f, 0.f};
;         cur = nxt; cA = nA; cB = nB; ++ui;
;         if constexpr (ALIGN_EPI) { if (wr == 1) PG8_BAR; }
;     __device__ __forceinline__ void operator()(const f32x4 (&acc)[2][2][4][2], const pg8::Unit& u, int wr, int wc, int fr, int fq) const {
;         const int row0 = u.pm * 256 + wr * 64 + fr, col = u.pn * 128 + wc * 32 + 8 * fq;
; #pragma unroll
;         for (int ai = 0; ai < 2; ++ai)
; #pragma unroll
;             for (int m = 0; m < 4; ++m) {
;                 const int row = row0 + ai * 128 + m * 16;
;                 const float rs = sumsq ? rsqrtf(sumsq[row] * (1.f / 1024.f) + EPS) : 1.f;
;                 float o[8];
; #pragma unroll
;                 for (int n = 0; n < 2; ++n)
; #pragma unroll
;                     for (int e = 0; e < 4; ++e) { const float g = acc[ai][0][m][n][e] * rs, up = acc[ai][1][m][n][e] * rs; o[4 * n + e] = silu_f(g) * up; }
;                 u32x4 w; w.x = pk2(o[0], o[1]); w.y = pk2(o[2], o[3]); w.z = pk2(o[4], o[5]); w.w = pk2(o[6], o[7]);
;                 *(u32x4*)(H + (size_t)row * DFF + col) = w;
;             }
	v_rcp_f32_e32 v57, v57
	v_rcp_f32_e32 v50, v50
	v_rcp_f32_e32 v51, v51
	v_rcp_f32_e32 v52, v52
	v_rcp_f32_e32 v53, v53
	v_rcp_f32_e32 v54, v54
	v_rcp_f32_e32 v55, v55
	v_rcp_f32_e32 v56, v56
	v_mul_f32_e32 v35, v35, v57
	v_mul_f32_e32 v49, v49, v50
	v_mul_f32_e32 v41, v41, v51
	v_mul_f32_e32 v45, v45, v52
	v_mul_f32_e32 v43, v43, v53
	v_mul_f32_e32 v47, v47, v54
	v_mul_f32_e32 v33, v33, v55
	v_mul_f32_e32 v37, v37, v56
	v_mul_f32_e32 v35, v34, v35
	v_mul_f32_e32 v48, v48, v49
	v_mul_f32_e32 v40, v40, v41
	v_mul_f32_e32 v41, v44, v45
	v_mul_f32_e32 v42, v42, v43
	v_mul_f32_e32 v43, v46, v47
	v_mul_f32_e32 v44, v32, v33
	v_mul_f32_e32 v36, v36, v37
	v_cvt_pk_bf16_f32 v32, v48, v40
	v_cvt_pk_bf16_f32 v33, v41, v42
	v_cvt_pk_bf16_f32 v34, v43, v44
	v_cvt_pk_bf16_f32 v35, v36, v35
	global_store_dwordx4 v[38:39], v[32:35], off
	s_nop 0
	s_nop 0
	v_mov_b32_e32 v33, v24
	v_mov_b32_e32 v24, v29
	v_mov_b32_e32 v29, v26
	v_mov_b32_e32 v26, v31
	v_mov_b32_e32 v31, v16
	v_mov_b32_e32 v16, v21
	v_mov_b32_e32 v21, v18
	v_mov_b32_e32 v18, v23
	v_mov_b32_e32 v32, v28
	v_mov_b32_e32 v28, v30
	v_mov_b32_e32 v30, v20
	v_mov_b32_e32 v20, v22
	v_add_u32_e32 v22, 0xa0, v144
	s_nop 0
	v_fmamk_f32 v23, v241, 0x3a800000, v154
	v_mul_f32_e32 v34, 0x4b800000, v23
	v_cmp_gt_f32_e32 vcc, s45, v23
	s_nop 1
	v_cndmask_b32_e32 v23, v23, v34, vcc
	v_rsq_f32_e32 v34, v23
	v_mad_i64_i32 v[22:23], s[0:1], v22, s46, v[120:121]
	v_lshl_add_u64 v[22:23], v[22:23], 0, v[122:123]
	v_mul_f32_e32 v35, 0x45800000, v34
	v_cndmask_b32_e32 v34, v34, v35, vcc
	v_pk_mul_f32 v[18:19], v[18:19], v[34:35] op_sel_hi:[1,0]
	v_pk_mul_f32 v[32:33], v[32:33], v[34:35] op_sel_hi:[1,0]
	v_pk_mul_f32 v[24:25], v[24:25], v[34:35] op_sel_hi:[1,0]
	v_pk_mul_f32 v[28:29], v[28:29], v[34:35] op_sel_hi:[1,0]
	v_pk_mul_f32 v[26:27], v[26:27], v[34:35] op_sel_hi:[1,0]
	v_pk_mul_f32 v[30:31], v[30:31], v[34:35] op_sel_hi:[1,0]
	v_pk_mul_f32 v[16:17], v[16:17], v[34:35] op_sel_hi:[1,0]
	v_pk_mul_f32 v[20:21], v[20:21], v[34:35] op_sel_hi:[1,0]
	v_mul_f32_e32 v41, 0xbfb8aa3b, v19
	v_mul_f32_e32 v34, 0xbfb8aa3b, v33
	v_mul_f32_e32 v35, 0xbfb8aa3b, v25
	v_mul_f32_e32 v36, 0xbfb8aa3b, v29
	v_mul_f32_e32 v37, 0xbfb8aa3b, v27
	v_mul_f32_e32 v38, 0xbfb8aa3b, v31
	v_mul_f32_e32 v39, 0xbfb8aa3b, v17
	v_mul_f32_e32 v40, 0xbfb8aa3b, v21
	v_exp_f32_e32 v41, v41
	v_exp_f32_e32 v34, v34
	v_exp_f32_e32 v35, v35
	v_exp_f32_e32 v36, v36
	v_exp_f32_e32 v37, v37
	v_exp_f32_e32 v38, v38
	v_exp_f32_e32 v39, v39
	v_exp_f32_e32 v40, v40
	v_add_f32_e32 v41, 1.0, v41
	v_add_f32_e32 v34, 1.0, v34
	v_add_f32_e32 v35, 1.0, v35
	v_add_f32_e32 v36, 1.0, v36
	v_add_f32_e32 v37, 1.0, v37
	v_add_f32_e32 v38, 1.0, v38
	v_add_f32_e32 v39, 1.0, v39
	v_add_f32_e32 v40, 1.0, v40
	v_rcp_f32_e32 v41, v41
	v_rcp_f32_e32 v34, v34
	v_rcp_f32_e32 v35, v35
	v_rcp_f32_e32 v36, v36
	v_rcp_f32_e32 v37, v37
	v_rcp_f32_e32 v38, v38
	v_rcp_f32_e32 v39, v39
	v_rcp_f32_e32 v40, v40
	v_mul_f32_e32 v19, v19, v41
	v_mul_f32_e32 v33, v33, v34
	v_mul_f32_e32 v25, v25, v35
	v_mul_f32_e32 v29, v29, v36
	v_mul_f32_e32 v27, v27, v37
	v_mul_f32_e32 v31, v31, v38
	v_mul_f32_e32 v17, v17, v39
	v_mul_f32_e32 v21, v21, v40
	v_mul_f32_e32 v19, v18, v19
	v_mul_f32_e32 v32, v32, v33
	v_mul_f32_e32 v24, v24, v25
	v_mul_f32_e32 v25, v28, v29
	v_mul_f32_e32 v26, v26, v27
	v_mul_f32_e32 v27, v30, v31
	v_mul_f32_e32 v28, v16, v17
	v_mul_f32_e32 v20, v20, v21
	v_cvt_pk_bf16_f32 v16, v32, v24
	v_cvt_pk_bf16_f32 v17, v25, v26
	v_cvt_pk_bf16_f32 v18, v27, v28
	v_cvt_pk_bf16_f32 v19, v20, v19
	global_store_dwordx4 v[22:23], v[16:19], off
	s_nop 0
	s_andn2_b64 vcc, exec, s[4:5]
	v_mov_b32_e32 v17, v8
	v_mov_b32_e32 v8, v13
	v_mov_b32_e32 v13, v10
	v_mov_b32_e32 v10, v15
	v_mov_b32_e32 v15, v0
	v_mov_b32_e32 v0, v5
	v_mov_b32_e32 v5, v2
	v_mov_b32_e32 v2, v7
	v_mov_b32_e32 v16, v12
	v_mov_b32_e32 v12, v14
	v_mov_b32_e32 v14, v4
	v_mov_b32_e32 v4, v6
	v_add_u32_e32 v6, 0xb0, v144
	s_nop 0
	v_fmamk_f32 v7, v242, 0x3a800000, v154
	v_mul_f32_e32 v18, 0x4b800000, v7
	v_cmp_gt_f32_e64 s[0:1], s45, v7
	s_nop 1
	v_cndmask_b32_e64 v7, v7, v18, s[0:1]
	v_rsq_f32_e32 v18, v7
	v_mad_i64_i32 v[6:7], s[22:23], v6, s46, v[120:121]
	v_lshl_add_u64 v[6:7], v[6:7], 0, v[122:123]
	v_mul_f32_e32 v19, 0x45800000, v18
	v_cndmask_b32_e64 v18, v18, v19, s[0:1]
	v_pk_mul_f32 v[2:3], v[2:3], v[18:19] op_sel_hi:[1,0]
	v_pk_mul_f32 v[16:17], v[16:17], v[18:19] op_sel_hi:[1,0]
	v_pk_mul_f32 v[8:9], v[8:9], v[18:19] op_sel_hi:[1,0]
	v_pk_mul_f32 v[12:13], v[12:13], v[18:19] op_sel_hi:[1,0]
	v_pk_mul_f32 v[10:11], v[10:11], v[18:19] op_sel_hi:[1,0]
	v_pk_mul_f32 v[14:15], v[14:15], v[18:19] op_sel_hi:[1,0]
	v_pk_mul_f32 v[0:1], v[0:1], v[18:19] op_sel_hi:[1,0]
	v_pk_mul_f32 v[4:5], v[4:5], v[18:19] op_sel_hi:[1,0]
	v_mul_f32_e32 v25, 0xbfb8aa3b, v3
	v_mul_f32_e32 v18, 0xbfb8aa3b, v17
	v_mul_f32_e32 v19, 0xbfb8aa3b, v9
	v_mul_f32_e32 v20, 0xbfb8aa3b, v13
	v_mul_f32_e32 v21, 0xbfb8aa3b, v11
	v_mul_f32_e32 v22, 0xbfb8aa3b, v15
	v_mul_f32_e32 v23, 0xbfb8aa3b, v1
	v_mul_f32_e32 v24, 0xbfb8aa3b, v5
	v_exp_f32_e32 v25, v25
	v_exp_f32_e32 v18, v18
	v_exp_f32_e32 v19, v19
	v_exp_f32_e32 v20, v20
	v_exp_f32_e32 v21, v21
	v_exp_f32_e32 v22, v22
	v_exp_f32_e32 v23, v23
	v_exp_f32_e32 v24, v24
	v_add_f32_e32 v25, 1.0, v25
	v_add_f32_e32 v18, 1.0, v18
	v_add_f32_e32 v19, 1.0, v19
	v_add_f32_e32 v20, 1.0, v20
	v_add_f32_e32 v21, 1.0, v21
	v_add_f32_e32 v22, 1.0, v22
	v_add_f32_e32 v23, 1.0, v23
	v_add_f32_e32 v24, 1.0, v24
	v_rcp_f32_e32 v25, v25
	v_rcp_f32_e32 v18, v18
	v_rcp_f32_e32 v19, v19
	v_rcp_f32_e32 v20, v20
	v_rcp_f32_e32 v21, v21
	v_rcp_f32_e32 v22, v22
	v_rcp_f32_e32 v23, v23
	v_rcp_f32_e32 v24, v24
	v_mul_f32_e32 v3, v3, v25
	v_mul_f32_e32 v17, v17, v18
	v_mul_f32_e32 v9, v9, v19
	v_mul_f32_e32 v13, v13, v20
	v_mul_f32_e32 v11, v11, v21
	v_mul_f32_e32 v15, v15, v22
	v_mul_f32_e32 v1, v1, v23
	v_mul_f32_e32 v5, v5, v24
	v_mul_f32_e32 v3, v2, v3
	s_mov_b64 s[0:1], -1
	v_mul_f32_e32 v16, v16, v17
	v_mul_f32_e32 v8, v8, v9
	v_mul_f32_e32 v9, v12, v13
	v_mul_f32_e32 v10, v10, v11
	v_mul_f32_e32 v11, v14, v15
	v_mul_f32_e32 v12, v0, v1
	v_mul_f32_e32 v4, v4, v5
	v_cvt_pk_bf16_f32 v0, v16, v8
	v_cvt_pk_bf16_f32 v1, v9, v10
	v_cvt_pk_bf16_f32 v2, v11, v12
	v_cvt_pk_bf16_f32 v3, v4, v3
	global_store_dwordx4 v[6:7], v[0:3], off
	s_cbranch_vccnz .LBB0_778
	s_andn2_b64 vcc, exec, s[2:3]
	s_cbranch_vccnz .LBB0_777
	s_barrier
	s_branch .LBB0_777

; __device__ __forceinline__ unsigned pk2(float lo, float hi) { return pg8::cvt_pk_bf16(lo, hi); }
;     __device__ __forceinline__ void operator()(const f32x4 (&acc)[2][2][4][2], const pg8::Unit& u, int wr, int wc, int fr, int fq) const {
;         const int row0 = u.pm * 256 + wr * 64 + fr, col0 = u.pn * 256 + wc * 32 + 8 * fq;
; #pragma unroll
;         for (int ai = 0; ai < 2; ++ai)
; #pragma unroll
;             for (int m = 0; m < 4; ++m) {
;                 const int row = row0 + ai * 128 + m * 16; float ss = 0.f;
; #pragma unroll
;                 for (int bj = 0; bj < 2; ++bj) {
;                     const size_t off = (size_t)row * DM + col0 + bj * 128;
;                     float o[8];
;                     if (BASE_BF16) { const u32x4 bw = *(const u32x4*)((const bf16_t*)base + off);
; #pragma unroll
;                         for (int e = 0; e < 4; ++e) { o[2 * e] = __uint_as_float(bw[e] << 16); o[2 * e + 1] = __uint_as_float(bw[e] & 0xffff0000u); } }
;                     else { const f32x4 b0 = *(const f32x4*)((const float*)base + off), b1 = *(const f32x4*)((const float*)base + off + 4);
; #pragma unroll
;                         for (int e = 0; e < 4; ++e) { o[e] = b0[e]; o[4 + e] = b1[e]; } }
; #pragma unroll
;                     for (int n = 0; n < 2; ++n)
; #pragma unroll
;                         for (int e = 0; e < 4; ++e) { const float v = o[4 * n + e] + alpha * acc[ai][bj][m][n][e]; o[4 * n + e] = v; ss += v * v; }
;                     if (OUT_BF16) { u32x4 w; w.x = pk2(o[0], o[1]); w.y = pk2(o[2], o[3]); w.z = pk2(o[4], o[5]); w.w = pk2(o[6], o[7]); *(u32x4*)((bf16_t*)out + off) = w; }
;                     else { *(f32x4*)((float*)out + off) = (f32x4){o[0], o[1], o[2], o[3]}; *(f32x4*)((float*)out + off + 4) = (f32x4){o[4], o[5], o[6], o[7]}; }
;                 }
.LBB0_865:
	v_lshl_add_u32 v148, s47, 8, v150
	v_lshl_or_b32 v146, s48, 8, v152
	v_ashrrev_i32_e32 v149, 31, v148
	v_ashrrev_i32_e32 v147, 31, v146
	v_lshlrev_b64 v[144:145], 10, v[148:149]
	v_lshl_add_u64 v[144:145], v[144:145], 0, v[146:147]
	v_lshlrev_b64 v[160:161], 1, v[144:145]
	v_lshl_add_u64 v[156:157], s[8:9], 0, v[160:161]
	s_mov_b64 s[98:99], 0x8000
	s_mov_b64 s[100:101], 0x28000
	v_mov_b32_e32 v232, v156
	v_mov_b32_e32 v233, v157
	global_load_dwordx4 v[168:171], v[232:233], off
	global_load_dwordx4 v[172:175], v[232:233], off offset:256
	v_lshl_add_u64 v[232:233], v[232:233], 0, s[98:99]
	global_load_dwordx4 v[176:179], v[232:233], off
	global_load_dwordx4 v[180:183], v[232:233], off offset:256
	v_lshl_add_u64 v[232:233], v[232:233], 0, s[98:99]
	global_load_dwordx4 v[184:187], v[232:233], off
	global_load_dwordx4 v[188:191], v[232:233], off offset:256
	v_lshl_add_u64 v[232:233], v[232:233], 0, s[98:99]
	global_load_dwordx4 v[192:195], v[232:233], off
	global_load_dwordx4 v[196:199], v[232:233], off offset:256
	v_lshl_add_u64 v[232:233], v[232:233], 0, s[100:101]
	global_load_dwordx4 v[200:203], v[232:233], off
	global_load_dwordx4 v[204:207], v[232:233], off offset:256
	v_lshl_add_u64 v[232:233], v[232:233], 0, s[98:99]
	global_load_dwordx4 v[208:211], v[232:233], off
	global_load_dwordx4 v[212:215], v[232:233], off offset:256
	v_lshl_add_u64 v[232:233], v[232:233], 0, s[98:99]
	global_load_dwordx4 v[216:219], v[232:233], off
	global_load_dwordx4 v[220:223], v[232:233], off offset:256
	v_lshl_add_u64 v[232:233], v[232:233], 0, s[98:99]
	global_load_dwordx4 v[224:227], v[232:233], off
	global_load_dwordx4 v[228:231], v[232:233], off offset:256
	v_readlane_b32 s24, v235, 2
	v_readlane_b32 s25, v235, 3
	v_or_b32_e32 v160, 0x100, v160
	v_lshl_add_u64 v[160:161], s[8:9], 0, v[160:161]
	v_lshl_add_u64 v[162:163], v[144:145], 2, s[24:25]
	s_and_b64 vcc, exec, s[0:1]
	s_mov_b64 s[0:1], -1
	v_readlane_b32 s26, v235, 4
	v_readlane_b32 s27, v235, 5
	s_waitcnt vmcnt(15)
	v_mov_b32_e32 v156, v168
	v_mov_b32_e32 v157, v169
	v_mov_b32_e32 v158, v170
	v_mov_b32_e32 v159, v171
	v_lshlrev_b32_e32 v164, 16, v156
	v_and_b32_e32 v165, 0xffff0000, v156
	v_lshlrev_b32_e32 v156, 16, v157
	v_and_b32_e32 v157, 0xffff0000, v157
	v_lshlrev_b32_e32 v166, 16, v158
	v_and_b32_e32 v167, 0xffff0000, v158
	v_lshlrev_b32_e32 v158, 16, v159
	v_and_b32_e32 v159, 0xffff0000, v159
	v_pk_fma_f32 v[124:125], v[124:125], 0.5, v[164:165] op_sel_hi:[1,0,1]
	v_pk_fma_f32 v[126:127], v[126:127], 0.5, v[156:157] op_sel_hi:[1,0,1]
	v_pk_fma_f32 v[120:121], v[120:121], 0.5, v[166:167] op_sel_hi:[1,0,1]
	v_pk_fma_f32 v[122:123], v[122:123], 0.5, v[158:159] op_sel_hi:[1,0,1]
	global_store_dwordx4 v[162:163], v[124:127], off
	global_store_dwordx4 v[162:163], v[120:123], off offset:16
	s_nop 0
	v_or_b32_e32 v124, 16, v148
	v_ashrrev_i32_e32 v125, 31, v124
	v_lshlrev_b64 v[124:125], 10, v[124:125]
	v_lshl_add_u64 v[124:125], v[124:125], 0, v[146:147]
	v_lshlrev_b64 v[126:127], 1, v[124:125]
	v_lshl_add_u64 v[156:157], s[8:9], 0, v[126:127]
	v_or_b32_e32 v126, 0x100, v126
	s_waitcnt vmcnt(16)
	v_mov_b32_e32 v120, v172
	v_mov_b32_e32 v121, v173
	v_mov_b32_e32 v122, v174
	v_mov_b32_e32 v123, v175
	v_lshlrev_b32_e32 v158, 16, v120
	v_and_b32_e32 v159, 0xffff0000, v120
	v_lshlrev_b32_e32 v120, 16, v121
	v_and_b32_e32 v121, 0xffff0000, v121
	v_lshlrev_b32_e32 v160, 16, v122
	v_and_b32_e32 v161, 0xffff0000, v122
	v_lshlrev_b32_e32 v122, 16, v123
	v_and_b32_e32 v123, 0xffff0000, v123
	v_pk_fma_f32 v[116:117], v[116:117], 0.5, v[158:159] op_sel_hi:[1,0,1]
	v_pk_fma_f32 v[118:119], v[118:119], 0.5, v[120:121] op_sel_hi:[1,0,1]
	v_pk_fma_f32 v[112:113], v[112:113], 0.5, v[160:161] op_sel_hi:[1,0,1]
	v_pk_fma_f32 v[114:115], v[114:115], 0.5, v[122:123] op_sel_hi:[1,0,1]
	global_store_dwordx4 v[162:163], v[116:119], off offset:512
	global_store_dwordx4 v[162:163], v[112:115], off offset:528
	s_nop 0
	v_lshl_add_u64 v[116:117], v[124:125], 2, s[24:25]
	v_lshl_add_u64 v[118:119], s[8:9], 0, v[126:127]
	s_waitcnt vmcnt(17)
	v_mov_b32_e32 v112, v176
	v_mov_b32_e32 v113, v177
	v_mov_b32_e32 v114, v178
	v_mov_b32_e32 v115, v179
	v_lshlrev_b32_e32 v120, 16, v112
	v_and_b32_e32 v121, 0xffff0000, v112
	v_lshlrev_b32_e32 v112, 16, v113
	v_and_b32_e32 v113, 0xffff0000, v113
	v_lshlrev_b32_e32 v122, 16, v114
	v_and_b32_e32 v123, 0xffff0000, v114
	v_lshlrev_b32_e32 v114, 16, v115
	v_and_b32_e32 v115, 0xffff0000, v115
	v_pk_fma_f32 v[108:109], v[108:109], 0.5, v[120:121] op_sel_hi:[1,0,1]
	v_pk_fma_f32 v[110:111], v[110:111], 0.5, v[112:113] op_sel_hi:[1,0,1]
	v_pk_fma_f32 v[104:105], v[104:105], 0.5, v[122:123] op_sel_hi:[1,0,1]
	v_pk_fma_f32 v[106:107], v[106:107], 0.5, v[114:115] op_sel_hi:[1,0,1]
	global_store_dwordx4 v[116:117], v[108:111], off
	global_store_dwordx4 v[116:117], v[104:107], off offset:16
	s_nop 0
	v_or_b32_e32 v108, 32, v148
	v_ashrrev_i32_e32 v109, 31, v108
	v_lshlrev_b64 v[108:109], 10, v[108:109]
	v_lshl_add_u64 v[108:109], v[108:109], 0, v[146:147]
	v_lshlrev_b64 v[110:111], 1, v[108:109]
	v_lshl_add_u64 v[112:113], s[8:9], 0, v[110:111]
	v_or_b32_e32 v110, 0x100, v110
	s_waitcnt vmcnt(18)
	v_mov_b32_e32 v104, v180
	v_mov_b32_e32 v105, v181
	v_mov_b32_e32 v106, v182
	v_mov_b32_e32 v107, v183
	v_lshlrev_b32_e32 v114, 16, v104
	v_and_b32_e32 v115, 0xffff0000, v104
	v_lshlrev_b32_e32 v104, 16, v105
	v_and_b32_e32 v105, 0xffff0000, v105
	v_lshlrev_b32_e32 v118, 16, v106
	v_and_b32_e32 v119, 0xffff0000, v106
	v_lshlrev_b32_e32 v106, 16, v107
	v_and_b32_e32 v107, 0xffff0000, v107
	v_pk_fma_f32 v[100:101], v[100:101], 0.5, v[114:115] op_sel_hi:[1,0,1]
	v_pk_fma_f32 v[102:103], v[102:103], 0.5, v[104:105] op_sel_hi:[1,0,1]
	v_pk_fma_f32 v[96:97], v[96:97], 0.5, v[118:119] op_sel_hi:[1,0,1]
	v_pk_fma_f32 v[98:99], v[98:99], 0.5, v[106:107] op_sel_hi:[1,0,1]
	global_store_dwordx4 v[116:117], v[100:103], off offset:512
	global_store_dwordx4 v[116:117], v[96:99], off offset:528
	s_nop 0
	v_lshl_add_u64 v[100:101], v[108:109], 2, s[24:25]
	v_lshl_add_u64 v[102:103], s[8:9], 0, v[110:111]
	s_waitcnt vmcnt(19)
; __device__ __forceinline__ unsigned pk2(float lo, float hi) { return pg8::cvt_pk_bf16(lo, hi); }
;     __device__ __forceinline__ void operator()(const f32x4 (&acc)[2][2][4][2], const pg8::Unit& u, int wr, int wc, int fr, int fq) const {
;         const int row0 = u.pm * 256 + wr * 64 + fr, col0 = u.pn * 256 + wc * 32 + 8 * fq;
; #pragma unroll
;         for (int ai = 0; ai < 2; ++ai)
; #pragma unroll
;             for (int m = 0; m < 4; ++m) {
;                 const int row = row0 + ai * 128 + m * 16; float ss = 0.f;
; #pragma unroll
;                 for (int bj = 0; bj < 2; ++bj) {
;                     const size_t off = (size_t)row * DM + col0 + bj * 128;
;                     float o[8];
;                     if (BASE_BF16) { const u32x4 bw = *(const u32x4*)((const bf16_t*)base + off);
; #pragma unroll
;                         for (int e = 0; e < 4; ++e) { o[2 * e] = __uint_as_float(bw[e] << 16); o[2 * e + 1] = __uint_as_float(bw[e] & 0xffff0000u); } }
;                     else { const f32x4 b0 = *(const f32x4*)((const float*)base + off), b1 = *(const f32x4*)((const float*)base + off + 4);
; #pragma unroll
;                         for (int e = 0; e < 4; ++e) { o[e] = b0[e]; o[4 + e] = b1[e]; } }
; #pragma unroll
;                     for (int n = 0; n < 2; ++n)
; #pragma unroll
;                         for (int e = 0; e < 4; ++e) { const float v = o[4 * n + e] + alpha * acc[ai][bj][m][n][e]; o[4 * n + e] = v; ss += v * v; }
;                     if (OUT_BF16) { u32x4 w; w.x = pk2(o[0], o[1]); w.y = pk2(o[2], o[3]); w.z = pk2(o[4], o[5]); w.w = pk2(o[6], o[7]); *(u32x4*)((bf16_t*)out + off) = w; }
;                     else { *(f32x4*)((float*)out + off) = (f32x4){o[0], o[1], o[2], o[3]}; *(f32x4*)((float*)out + off + 4) = (f32x4){o[4], o[5], o[6], o[7]}; }
;                 }
	v_mov_b32_e32 v96, v184
	v_mov_b32_e32 v97, v185
	v_mov_b32_e32 v98, v186
	v_mov_b32_e32 v99, v187
	v_lshlrev_b32_e32 v104, 16, v96
	v_and_b32_e32 v105, 0xffff0000, v96
	v_lshlrev_b32_e32 v96, 16, v97
	v_and_b32_e32 v97, 0xffff0000, v97
	v_lshlrev_b32_e32 v106, 16, v98
	v_and_b32_e32 v107, 0xffff0000, v98
	v_lshlrev_b32_e32 v98, 16, v99
	v_and_b32_e32 v99, 0xffff0000, v99
	v_pk_fma_f32 v[92:93], v[92:93], 0.5, v[104:105] op_sel_hi:[1,0,1]
	v_pk_fma_f32 v[94:95], v[94:95], 0.5, v[96:97] op_sel_hi:[1,0,1]
	v_pk_fma_f32 v[88:89], v[88:89], 0.5, v[106:107] op_sel_hi:[1,0,1]
	v_pk_fma_f32 v[90:91], v[90:91], 0.5, v[98:99] op_sel_hi:[1,0,1]
	global_store_dwordx4 v[100:101], v[92:95], off
	global_store_dwordx4 v[100:101], v[88:91], off offset:16
	s_nop 0
	v_or_b32_e32 v92, 48, v148
	v_ashrrev_i32_e32 v93, 31, v92
	v_lshlrev_b64 v[92:93], 10, v[92:93]
	v_lshl_add_u64 v[92:93], v[92:93], 0, v[146:147]
	v_lshlrev_b64 v[94:95], 1, v[92:93]
	v_lshl_add_u64 v[96:97], s[8:9], 0, v[94:95]
	v_or_b32_e32 v94, 0x100, v94
	s_waitcnt vmcnt(20)
	v_mov_b32_e32 v88, v188
	v_mov_b32_e32 v89, v189
	v_mov_b32_e32 v90, v190
	v_mov_b32_e32 v91, v191
	v_lshlrev_b32_e32 v98, 16, v88
	v_and_b32_e32 v99, 0xffff0000, v88
	v_lshlrev_b32_e32 v88, 16, v89
	v_and_b32_e32 v89, 0xffff0000, v89
	v_lshlrev_b32_e32 v102, 16, v90
	v_and_b32_e32 v103, 0xffff0000, v90
	v_lshlrev_b32_e32 v90, 16, v91
	v_and_b32_e32 v91, 0xffff0000, v91
	v_pk_fma_f32 v[84:85], v[84:85], 0.5, v[98:99] op_sel_hi:[1,0,1]
	v_pk_fma_f32 v[86:87], v[86:87], 0.5, v[88:89] op_sel_hi:[1,0,1]
	v_pk_fma_f32 v[80:81], v[80:81], 0.5, v[102:103] op_sel_hi:[1,0,1]
	v_pk_fma_f32 v[82:83], v[82:83], 0.5, v[90:91] op_sel_hi:[1,0,1]
	global_store_dwordx4 v[100:101], v[84:87], off offset:512
	global_store_dwordx4 v[100:101], v[80:83], off offset:528
	s_nop 0
	v_lshl_add_u64 v[84:85], v[92:93], 2, s[24:25]
	v_lshl_add_u64 v[86:87], s[8:9], 0, v[94:95]
	s_waitcnt vmcnt(21)
	v_mov_b32_e32 v80, v192
	v_mov_b32_e32 v81, v193
	v_mov_b32_e32 v82, v194
	v_mov_b32_e32 v83, v195
	v_lshlrev_b32_e32 v88, 16, v80
	v_and_b32_e32 v89, 0xffff0000, v80
	v_lshlrev_b32_e32 v80, 16, v81
	v_and_b32_e32 v81, 0xffff0000, v81
	v_lshlrev_b32_e32 v90, 16, v82
	v_and_b32_e32 v91, 0xffff0000, v82
	v_lshlrev_b32_e32 v82, 16, v83
	v_and_b32_e32 v83, 0xffff0000, v83
	v_pk_fma_f32 v[76:77], v[76:77], 0.5, v[88:89] op_sel_hi:[1,0,1]
	v_pk_fma_f32 v[78:79], v[78:79], 0.5, v[80:81] op_sel_hi:[1,0,1]
	v_pk_fma_f32 v[72:73], v[72:73], 0.5, v[90:91] op_sel_hi:[1,0,1]
	v_pk_fma_f32 v[74:75], v[74:75], 0.5, v[82:83] op_sel_hi:[1,0,1]
	global_store_dwordx4 v[84:85], v[76:79], off
	global_store_dwordx4 v[84:85], v[72:75], off offset:16
	s_nop 0
	v_lshl_add_u64 v[76:77], v[144:145], 0, s[12:13]
	v_lshlrev_b64 v[78:79], 1, v[76:77]
	v_lshl_add_u64 v[80:81], s[8:9], 0, v[78:79]
	v_or_b32_e32 v78, 0x100, v78
	s_waitcnt vmcnt(22)
	v_mov_b32_e32 v72, v196
	v_mov_b32_e32 v73, v197
	v_mov_b32_e32 v74, v198
	v_mov_b32_e32 v75, v199
	v_lshlrev_b32_e32 v82, 16, v72
	v_and_b32_e32 v83, 0xffff0000, v72
	v_lshlrev_b32_e32 v72, 16, v73
	v_and_b32_e32 v73, 0xffff0000, v73
	v_lshlrev_b32_e32 v86, 16, v74
	v_and_b32_e32 v87, 0xffff0000, v74
	v_lshlrev_b32_e32 v74, 16, v75
	v_and_b32_e32 v75, 0xffff0000, v75
	v_pk_fma_f32 v[68:69], v[68:69], 0.5, v[82:83] op_sel_hi:[1,0,1]
	v_pk_fma_f32 v[70:71], v[70:71], 0.5, v[72:73] op_sel_hi:[1,0,1]
	v_pk_fma_f32 v[64:65], v[64:65], 0.5, v[86:87] op_sel_hi:[1,0,1]
	v_pk_fma_f32 v[66:67], v[66:67], 0.5, v[74:75] op_sel_hi:[1,0,1]
	global_store_dwordx4 v[84:85], v[68:71], off offset:512
	global_store_dwordx4 v[84:85], v[64:67], off offset:528
	s_nop 0
	v_lshl_add_u64 v[68:69], v[76:77], 2, s[24:25]
	v_lshl_add_u64 v[70:71], s[8:9], 0, v[78:79]
	s_waitcnt vmcnt(23)
	v_mov_b32_e32 v64, v200
	v_mov_b32_e32 v65, v201
	v_mov_b32_e32 v66, v202
	v_mov_b32_e32 v67, v203
	v_lshlrev_b32_e32 v72, 16, v64
	v_and_b32_e32 v73, 0xffff0000, v64
	v_lshlrev_b32_e32 v64, 16, v65
	v_and_b32_e32 v65, 0xffff0000, v65
	v_lshlrev_b32_e32 v74, 16, v66
	v_and_b32_e32 v75, 0xffff0000, v66
	v_lshlrev_b32_e32 v66, 16, v67
	v_and_b32_e32 v67, 0xffff0000, v67
	v_pk_fma_f32 v[60:61], v[60:61], 0.5, v[72:73] op_sel_hi:[1,0,1]
	v_pk_fma_f32 v[62:63], v[62:63], 0.5, v[64:65] op_sel_hi:[1,0,1]
	v_pk_fma_f32 v[56:57], v[56:57], 0.5, v[74:75] op_sel_hi:[1,0,1]
	v_pk_fma_f32 v[58:59], v[58:59], 0.5, v[66:67] op_sel_hi:[1,0,1]
	global_store_dwordx4 v[68:69], v[60:63], off
	global_store_dwordx4 v[68:69], v[56:59], off offset:16
	s_nop 0
	v_lshl_add_u64 v[60:61], v[144:145], 0, s[14:15]
	v_lshlrev_b64 v[62:63], 1, v[60:61]
	v_lshl_add_u64 v[64:65], s[8:9], 0, v[62:63]
	v_or_b32_e32 v62, 0x100, v62
	s_waitcnt vmcnt(24)
	v_mov_b32_e32 v56, v204
	v_mov_b32_e32 v57, v205
	v_mov_b32_e32 v58, v206
	v_mov_b32_e32 v59, v207
	v_lshlrev_b32_e32 v66, 16, v56
	v_and_b32_e32 v67, 0xffff0000, v56
	v_lshlrev_b32_e32 v56, 16, v57
	v_and_b32_e32 v57, 0xffff0000, v57
	v_lshlrev_b32_e32 v70, 16, v58
	v_and_b32_e32 v71, 0xffff0000, v58
	v_lshlrev_b32_e32 v58, 16, v59
	v_and_b32_e32 v59, 0xffff0000, v59
	v_pk_fma_f32 v[52:53], v[52:53], 0.5, v[66:67] op_sel_hi:[1,0,1]
	v_pk_fma_f32 v[54:55], v[54:55], 0.5, v[56:57] op_sel_hi:[1,0,1]
	v_pk_fma_f32 v[48:49], v[48:49], 0.5, v[70:71] op_sel_hi:[1,0,1]
	v_pk_fma_f32 v[50:51], v[50:51], 0.5, v[58:59] op_sel_hi:[1,0,1]
	global_store_dwordx4 v[68:69], v[52:55], off offset:512
	global_store_dwordx4 v[68:69], v[48:51], off offset:528
	s_nop 0
	v_lshl_add_u64 v[52:53], v[60:61], 2, s[24:25]
	v_lshl_add_u64 v[54:55], s[8:9], 0, v[62:63]
	s_waitcnt vmcnt(25)
; #define PG8_BAR __builtin_amdgcn_s_barrier()
; template <class Epi, class Sched, bool ALIGN_EPI = false, bool SP2 = false>
; __device__ __forceinline__ void gemm_phase(PG8_LAS unsigned char* lds, const Gemm g, const Sched& S, const Epi& E) {
;     ...
;         if (!has_next) break;
; #pragma unroll
;         for (int a = 0; a < 2; ++a)
; #pragma unroll
;             for (int b = 0; b < 2; ++b)
; #pragma unroll
;                 for (int m = 0; m < 4; ++m)
; #pragma unroll
;                     for (int n = 0; n < 2; ++n) acc[a][b][m][n] = (f32x4){0.f, 0.f, 0.f, 0.f};
;         cur = nxt; cA = nA; cB = nB; ++ui;
;         if constexpr (ALIGN_EPI) { if (wr == 1) PG8_BAR; }
;     __device__ __forceinline__ void operator()(const f32x4 (&acc)[2][2][4][2], const pg8::Unit& u, int wr, int wc, int fr, int fq) const {
;         const int row0 = u.pm * 256 + wr * 64 + fr, col0 = u.pn * 256 + wc * 32 + 8 * fq;
; #pragma unroll
;         for (int ai = 0; ai < 2; ++ai)
; #pragma unroll
;             for (int m = 0; m < 4; ++m) {
;                 const int row = row0 + ai * 128 + m * 16; float ss = 0.f;
; #pragma unroll
;                 for (int bj = 0; bj < 2; ++bj) {
;                     const size_t off = (size_t)row * DM + col0 + bj * 128;
;                     float o[8];
;                     if (BASE_BF16) { const u32x4 bw = *(const u32x4*)((const bf16_t*)base + off);
; #pragma unroll
;                         for (int e = 0; e < 4; ++e) { o[2 * e] = __uint_as_float(bw[e] << 16); o[2 * e + 1] = __uint_as_float(bw[e] & 0xffff0000u); } }
;                     else { const f32x4 b0 = *(const f32x4*)((const float*)base + off), b1 = *(const f32x4*)((const float*)base + off + 4);
; #pragma unroll
;                         for (int e = 0; e < 4; ++e) { o[e] = b0[e]; o[4 + e] = b1[e]; } }
; #pragma unroll
;                     for (int n = 0; n < 2; ++n)
; #pragma unroll
;                         for (int e = 0; e < 4; ++e) { const float v = o[4 * n + e] + alpha * acc[ai][bj][m][n][e]; o[4 * n + e] = v; ss += v * v; }
;                     if (OUT_BF16) { u32x4 w; w.x = pk2(o[0], o[1]); w.y = pk2(o[2], o[3]); w.z = pk2(o[4], o[5]); w.w = pk2(o[6], o[7]); *(u32x4*)((bf16_t*)out + off) = w; }
;                     else { *(f32x4*)((float*)out + off) = (f32x4){o[0], o[1], o[2], o[3]}; *(f32x4*)((float*)out + off + 4) = (f32x4){o[4], o[5], o[6], o[7]}; }
;                 }
	v_mov_b32_e32 v48, v208
	v_mov_b32_e32 v49, v209
	v_mov_b32_e32 v50, v210
	v_mov_b32_e32 v51, v211
	v_lshlrev_b32_e32 v56, 16, v48
	v_and_b32_e32 v57, 0xffff0000, v48
	v_lshlrev_b32_e32 v48, 16, v49
	v_and_b32_e32 v49, 0xffff0000, v49
	v_lshlrev_b32_e32 v58, 16, v50
	v_and_b32_e32 v59, 0xffff0000, v50
	v_lshlrev_b32_e32 v50, 16, v51
	v_and_b32_e32 v51, 0xffff0000, v51
	v_pk_fma_f32 v[44:45], v[44:45], 0.5, v[56:57] op_sel_hi:[1,0,1]
	v_pk_fma_f32 v[46:47], v[46:47], 0.5, v[48:49] op_sel_hi:[1,0,1]
	v_pk_fma_f32 v[40:41], v[40:41], 0.5, v[58:59] op_sel_hi:[1,0,1]
	v_pk_fma_f32 v[42:43], v[42:43], 0.5, v[50:51] op_sel_hi:[1,0,1]
	global_store_dwordx4 v[52:53], v[44:47], off
	global_store_dwordx4 v[52:53], v[40:43], off offset:16
	s_nop 0
	v_lshl_add_u64 v[44:45], v[144:145], 0, s[16:17]
	v_lshlrev_b64 v[46:47], 1, v[44:45]
	v_lshl_add_u64 v[48:49], s[8:9], 0, v[46:47]
	v_or_b32_e32 v46, 0x100, v46
	s_waitcnt vmcnt(26)
	v_mov_b32_e32 v40, v212
	v_mov_b32_e32 v41, v213
	v_mov_b32_e32 v42, v214
	v_mov_b32_e32 v43, v215
	v_lshlrev_b32_e32 v50, 16, v40
	v_and_b32_e32 v51, 0xffff0000, v40
	v_lshlrev_b32_e32 v40, 16, v41
	v_and_b32_e32 v41, 0xffff0000, v41
	v_lshlrev_b32_e32 v54, 16, v42
	v_and_b32_e32 v55, 0xffff0000, v42
	v_lshlrev_b32_e32 v42, 16, v43
	v_and_b32_e32 v43, 0xffff0000, v43
	v_pk_fma_f32 v[36:37], v[36:37], 0.5, v[50:51] op_sel_hi:[1,0,1]
	v_pk_fma_f32 v[38:39], v[38:39], 0.5, v[40:41] op_sel_hi:[1,0,1]
	v_pk_fma_f32 v[32:33], v[32:33], 0.5, v[54:55] op_sel_hi:[1,0,1]
	v_pk_fma_f32 v[34:35], v[34:35], 0.5, v[42:43] op_sel_hi:[1,0,1]
	global_store_dwordx4 v[52:53], v[36:39], off offset:512
	global_store_dwordx4 v[52:53], v[32:35], off offset:528
	s_nop 0
	v_lshl_add_u64 v[36:37], v[44:45], 2, s[24:25]
	v_lshl_add_u64 v[38:39], s[8:9], 0, v[46:47]
	s_waitcnt vmcnt(27)
	v_mov_b32_e32 v32, v216
	v_mov_b32_e32 v33, v217
	v_mov_b32_e32 v34, v218
	v_mov_b32_e32 v35, v219
	v_lshlrev_b32_e32 v40, 16, v32
	v_and_b32_e32 v41, 0xffff0000, v32
	v_lshlrev_b32_e32 v32, 16, v33
	v_and_b32_e32 v33, 0xffff0000, v33
	v_lshlrev_b32_e32 v42, 16, v34
	v_and_b32_e32 v43, 0xffff0000, v34
	v_lshlrev_b32_e32 v34, 16, v35
	v_and_b32_e32 v35, 0xffff0000, v35
	v_pk_fma_f32 v[28:29], v[28:29], 0.5, v[40:41] op_sel_hi:[1,0,1]
	v_pk_fma_f32 v[30:31], v[30:31], 0.5, v[32:33] op_sel_hi:[1,0,1]
	v_pk_fma_f32 v[24:25], v[24:25], 0.5, v[42:43] op_sel_hi:[1,0,1]
	v_pk_fma_f32 v[26:27], v[26:27], 0.5, v[34:35] op_sel_hi:[1,0,1]
	global_store_dwordx4 v[36:37], v[28:31], off
	global_store_dwordx4 v[36:37], v[24:27], off offset:16
	s_nop 0
	v_lshl_add_u64 v[28:29], v[144:145], 0, s[18:19]
	v_lshlrev_b64 v[30:31], 1, v[28:29]
	v_lshl_add_u64 v[32:33], s[8:9], 0, v[30:31]
	v_or_b32_e32 v30, 0x100, v30
	s_waitcnt vmcnt(28)
	v_mov_b32_e32 v24, v220
	v_mov_b32_e32 v25, v221
	v_mov_b32_e32 v26, v222
	v_mov_b32_e32 v27, v223
	v_lshlrev_b32_e32 v34, 16, v24
	v_and_b32_e32 v35, 0xffff0000, v24
	v_lshlrev_b32_e32 v24, 16, v25
	v_and_b32_e32 v25, 0xffff0000, v25
	v_lshlrev_b32_e32 v38, 16, v26
	v_and_b32_e32 v39, 0xffff0000, v26
	v_lshlrev_b32_e32 v26, 16, v27
	v_and_b32_e32 v27, 0xffff0000, v27
	v_pk_fma_f32 v[20:21], v[20:21], 0.5, v[34:35] op_sel_hi:[1,0,1]
	v_pk_fma_f32 v[22:23], v[22:23], 0.5, v[24:25] op_sel_hi:[1,0,1]
	v_pk_fma_f32 v[16:17], v[16:17], 0.5, v[38:39] op_sel_hi:[1,0,1]
	v_pk_fma_f32 v[18:19], v[18:19], 0.5, v[26:27] op_sel_hi:[1,0,1]
	global_store_dwordx4 v[36:37], v[20:23], off offset:512
	global_store_dwordx4 v[36:37], v[16:19], off offset:528
	s_nop 0
	v_lshl_add_u64 v[20:21], v[28:29], 2, s[24:25]
	v_lshl_add_u64 v[22:23], s[8:9], 0, v[30:31]
	s_waitcnt vmcnt(29)
	v_mov_b32_e32 v16, v224
	v_mov_b32_e32 v17, v225
	v_mov_b32_e32 v18, v226
	v_mov_b32_e32 v19, v227
	v_lshlrev_b32_e32 v24, 16, v16
	v_and_b32_e32 v25, 0xffff0000, v16
	v_lshlrev_b32_e32 v16, 16, v17
	v_and_b32_e32 v17, 0xffff0000, v17
	v_lshlrev_b32_e32 v26, 16, v18
	v_and_b32_e32 v27, 0xffff0000, v18
	v_lshlrev_b32_e32 v18, 16, v19
	v_and_b32_e32 v19, 0xffff0000, v19
	v_pk_fma_f32 v[12:13], v[12:13], 0.5, v[24:25] op_sel_hi:[1,0,1]
	v_pk_fma_f32 v[14:15], v[14:15], 0.5, v[16:17] op_sel_hi:[1,0,1]
	v_pk_fma_f32 v[8:9], v[8:9], 0.5, v[26:27] op_sel_hi:[1,0,1]
	v_pk_fma_f32 v[10:11], v[10:11], 0.5, v[18:19] op_sel_hi:[1,0,1]
	global_store_dwordx4 v[20:21], v[12:15], off
	global_store_dwordx4 v[20:21], v[8:11], off offset:16
	s_nop 0
	s_waitcnt vmcnt(30)
	v_mov_b32_e32 v8, v228
	v_mov_b32_e32 v9, v229
	v_mov_b32_e32 v10, v230
	v_mov_b32_e32 v11, v231
	v_lshlrev_b32_e32 v12, 16, v8
	v_and_b32_e32 v13, 0xffff0000, v8
	v_lshlrev_b32_e32 v8, 16, v9
	v_and_b32_e32 v9, 0xffff0000, v9
	v_lshlrev_b32_e32 v14, 16, v10
	v_and_b32_e32 v15, 0xffff0000, v10
	v_lshlrev_b32_e32 v10, 16, v11
	v_and_b32_e32 v11, 0xffff0000, v11
	v_pk_fma_f32 v[4:5], v[4:5], 0.5, v[12:13] op_sel_hi:[1,0,1]
	v_pk_fma_f32 v[6:7], v[6:7], 0.5, v[8:9] op_sel_hi:[1,0,1]
	v_pk_fma_f32 v[0:1], v[0:1], 0.5, v[14:15] op_sel_hi:[1,0,1]
	v_pk_fma_f32 v[2:3], v[2:3], 0.5, v[10:11] op_sel_hi:[1,0,1]
	global_store_dwordx4 v[20:21], v[4:7], off offset:512
	global_store_dwordx4 v[20:21], v[0:3], off offset:528
	s_cbranch_vccnz .LBB0_850
	s_andn2_b64 vcc, exec, s[2:3]
	s_cbranch_vccnz .LBB0_849
	s_barrier
	s_branch .LBB0_849

; #define LAS __attribute__((address_space(3)))
; __global__ void __launch_bounds__(512, 2) mega(Args a) {
;     extern __shared__ __attribute__((aligned(16))) unsigned char lds_raw[];
;     LAS unsigned char* lds = (LAS unsigned char*)lds_raw;
	.amdhsa_kernel _Z4mega4Args
		.amdhsa_group_segment_fixed_size 0
		.amdhsa_private_segment_fixed_size 0
		.amdhsa_kernarg_size 432
		.amdhsa_user_sgpr_count 2
		.amdhsa_user_sgpr_dispatch_ptr 0
		.amdhsa_user_sgpr_queue_ptr 0
		.amdhsa_user_sgpr_kernarg_segment_ptr 1
		.amdhsa_user_sgpr_dispatch_id 0
		.amdhsa_user_sgpr_kernarg_preload_length 0
		.amdhsa_user_sgpr_kernarg_preload_offset 0
		.amdhsa_user_sgpr_private_segment_size 0
		.amdhsa_uses_dynamic_stack 0
		.amdhsa_enable_private_segment 0
		.amdhsa_system_sgpr_workgroup_id_x 1
		.amdhsa_system_sgpr_workgroup_id_y 0
		.amdhsa_system_sgpr_workgroup_id_z 0
		.amdhsa_system_sgpr_workgroup_info 0
		.amdhsa_system_vgpr_workitem_id 2
		.amdhsa_next_free_vgpr 244
		.amdhsa_next_free_sgpr 102
		.amdhsa_accum_offset 244
		.amdhsa_reserve_vcc 1
		.amdhsa_float_round_mode_32 0
		.amdhsa_float_round_mode_16_64 0
		.amdhsa_float_denorm_mode_32 3
		.amdhsa_float_denorm_mode_16_64 3
		.amdhsa_dx10_clamp 1
		.amdhsa_ieee_mode 1
		.amdhsa_fp16_overflow 0
		.amdhsa_tg_split 0
		.amdhsa_exception_fp_ieee_invalid_op 0
		.amdhsa_exception_fp_denorm_src 0
		.amdhsa_exception_fp_ieee_div_zero 0
		.amdhsa_exception_fp_ieee_overflow 0
		.amdhsa_exception_fp_ieee_underflow 0
		.amdhsa_exception_fp_ieee_inexact 0
		.amdhsa_exception_int_div_zero 0
	.end_amdhsa_kernel

amdhsa.kernels:
  - .agpr_count:     0
    .args:
      - .offset:         0
        .size:           176
        .value_kind:     by_value
      - .offset:         176
        .size:           4
        .value_kind:     hidden_block_count_x
      - .offset:         180
        .size:           4
        .value_kind:     hidden_block_count_y
      - .offset:         184
        .size:           4
        .value_kind:     hidden_block_count_z
      - .offset:         188
        .size:           2
        .value_kind:     hidden_group_size_x
      - .offset:         190
        .size:           2
        .value_kind:     hidden_group_size_y
      - .offset:         192
        .size:           2
        .value_kind:     hidden_group_size_z
      - .offset:         194
        .size:           2
        .value_kind:     hidden_remainder_x
      - .offset:         196
        .size:           2
        .value_kind:     hidden_remainder_y
      - .offset:         198
        .size:           2
        .value_kind:     hidden_remainder_z
      - .offset:         216
        .size:           8
        .value_kind:     hidden_global_offset_x
      - .offset:         224
        .size:           8
        .value_kind:     hidden_global_offset_y
      - .offset:         232
        .size:           8
        .value_kind:     hidden_global_offset_z
      - .offset:         240
        .size:           2
        .value_kind:     hidden_grid_dims
      - .offset:         264
        .size:           8
        .value_kind:     hidden_multigrid_sync_arg
      - .offset:         296
        .size:           4
        .value_kind:     hidden_dynamic_lds_size
    .group_segment_fixed_size: 0
    .kernarg_segment_align: 8
    .kernarg_segment_size: 432
    .language:       OpenCL C
    .language_version:
      - 2
      - 0
    .max_flat_workgroup_size: 512
    .name:           _Z4mega4Args
    .private_segment_fixed_size: 0
    .sgpr_count:     108
    .sgpr_spill_count: 86
    .symbol:         _Z4mega4Args.kd
    .uniform_work_group_size: 1
    .uses_dynamic_stack: false
    .vgpr_count:     244
    .vgpr_spill_count: 0
    .wavefront_size: 64
